# attention: per-step barrier moved up to just behind the last V-fragment read (before the 4th PV MFMA group); five of the next step's K-fragment reads issued right behind it, the other three behind the
# speedup vs baseline: 1.0149x; 1.0149x over previous
; template <bool FIRST, bool HAS_PREV> ...
;     ...
;     { const float nm = FIRST ? 0.f : -st.mrun;
; #pragma unroll
;       for (int i = 0; i < 16; ++i) { c0[i] = nm; c1[i] = nm; } }
; #pragma unroll
;     for (int ks = 0; ks < 2; ++ks) { DSR128(kf[2 * ks], ka[ks], 0); DSR128(kf[2 * ks + 1], ka[ks], 4096); }
;     asm volatile("s_waitcnt lgkmcnt(0)" : "+v"(kf[0]), "+v"(kf[1]), "+v"(kf[2]), "+v"(kf[3]));
; #pragma unroll
;     for (int ks = 0; ks < 2; ++ks) {
;         c0 = __builtin_amdgcn_mfma_f32_32x32x16_bf16(kf[2 * ks], qr[ks], c0, 0, 0, 0);
;         c1 = __builtin_amdgcn_mfma_f32_32x32x16_bf16(kf[2 * ks + 1], qr[ks], c1, 0, 0, 0);
;     }
;     __builtin_amdgcn_sched_barrier(0);
;     { bf16x8 kg[4];
; #pragma unroll
;       for (int ks = 0; ks < 2; ++ks) { DSR128(kg[2 * ks], ka[2 + ks], 0); DSR128(kg[2 * ks + 1], ka[2 + ks], 4096); }
;       asm volatile("s_waitcnt lgkmcnt(0)" : "+v"(kg[0]), "+v"(kg[1]), "+v"(kg[2]), "+v"(kg[3]));
; #pragma unroll
;       for (int ks = 0; ks < 2; ++ks) {
;           c0 = __builtin_amdgcn_mfma_f32_32x32x16_bf16(kg[2 * ks], qr[2 + ks], c0, 0, 0, 0);
; __device__ __forceinline__ void attn_unit(LAS unsigned char* lds, const bf16* __restrict__ Qb, const bf16* __restrict__ Kb, const bf16* __restrict__ VT, bf16* __restrict__ Y,
;                                           const float* __restrict__ gsub, float lam, int b, int h, int qb, float* o1scr) {
;     ...
;     for (int mp = 0; mp < 2; ++mp) {
;         const int c1 = 256 * (h >> 1) + 32 * (2 * (h & 1) + mp);
;         const bf16* qp = Qb + (tok0 + (size_t)qb * 256 + wid * 32 + r32) * 512 + c1 + 8 * hi;
;         bf16x8 qr[4];
;         qr[0] = *(const bf16x8*)(qp); qr[1] = *(const bf16x8*)(qp + 16); qr[2] = *(const bf16x8*)(qp + 128); qr[3] = *(const bf16x8*)(qp + 144);
;         const bf16* kp = Kb + (tok0 + lrow) * 512 + c1 + kcol;
;         const bf16* vp = VT + ((size_t)((b * 4 + h) * 32) * 128 + lrow) * 64 + lc * 8;
;         ATT_DMA(kp, 0); ATT_DMA(vp, VB0); ATT_DMA(vp + 4096, VB0 + 8192); ATT_DMA(kp + (size_t)64 * 512, KSL);
;         ATT_WAITBAR(0);
; #pragma unroll
;         for (int e = 0; e < 4; ++e)
; #pragma unroll
;             for (int i = 0; i < 16; ++i) o[e][i] = 0.f;
;         AttnState st; st.mrun = 0.f; st.l = 0.f;
;         bf16x8 pbp[4];
;         f32x16 sA, sB;
;         int s0 = 0, s1 = 1, s2 = 2;
;     ...
;         ATT_STEP(0, true, false);
.LBB0_560:
	s_or_b32 s44, s73, s44
	s_lshl_b64 s[82:83], s[44:45], 1
	v_lshl_add_u64 v[0:1], v[176:177], 0, s[82:83]
	global_load_dwordx4 v[96:99], v[0:1], off
	s_mov_b32 m0, s33
	v_lshl_add_u64 v[2:3], v[180:181], 0, s[82:83]
	global_load_dwordx4 v[100:103], v[0:1], off offset:32
	global_load_dwordx4 v[104:107], v[0:1], off offset:256
	global_load_dwordx4 v[108:111], v[0:1], off offset:288
	v_lshl_add_u64 v[0:1], v[2:3], 0, s[62:63]
	global_load_lds_dwordx4 v[2:3], off
	s_mov_b32 m0, s89
	v_lshl_add_u64 v[2:3], v[2:3], 0, s[64:65]
	global_load_lds_dwordx4 v[184:185], off
	s_mov_b32 m0, s90
	s_mov_b32 s44, s45
	global_load_lds_dwordx4 v[186:187], off
	s_mov_b32 m0, s91
	s_mov_b32 s46, s45
	global_load_lds_dwordx4 v[0:1], off
	s_waitcnt vmcnt(0) lgkmcnt(0)
	s_barrier
	s_mov_b32 m0, s92
	s_mov_b32 s47, s45
	global_load_lds_dwordx4 v[2:3], off
	s_mov_b32 m0, s93
	s_mov_b32 s48, s45
	global_load_lds_dwordx4 v[188:189], off
	s_mov_b32 m0, s94
	s_mov_b32 s49, s45
	global_load_lds_dwordx4 v[190:191], off
	ds_read_b128 v[0:3], v217 offset:0
	ds_read_b128 v[4:7], v217 offset:0x1000
	ds_read_b128 v[8:11], v218 offset:0
	ds_read_b128 v[48:51], v218 offset:0x1000
	s_mov_b32 s50, s45
	s_waitcnt lgkmcnt(0)
	s_mov_b32 s51, s45
	s_mov_b32 s52, s45
	s_mov_b32 s53, s45
	s_mov_b32 s54, s45
	s_mov_b32 s55, s45
	s_mov_b32 s56, s45
	s_mov_b32 s57, s45
	s_mov_b32 s58, s45
	s_mov_b32 s59, s45
	s_mov_b32 s74, 1
	s_waitcnt vmcnt(3)
	v_mfma_f32_32x32x16_bf16 v[16:31], v[0:3], v[96:99], 0
	v_mfma_f32_32x32x16_bf16 v[32:47], v[4:7], v[96:99], 0
	v_mfma_f32_32x32x16_bf16 v[16:31], v[8:11], v[100:103], v[16:31]
	v_mov_b64_e32 v[0:1], s[44:45]
	v_mov_b64_e32 v[2:3], s[46:47]
	v_mov_b64_e32 v[4:5], s[48:49]
	v_mov_b64_e32 v[6:7], s[50:51]
	v_mov_b64_e32 v[8:9], s[52:53]
	v_mov_b64_e32 v[10:11], s[54:55]
	v_mov_b64_e32 v[12:13], s[56:57]
	v_mfma_f32_32x32x16_bf16 v[32:47], v[48:51], v[100:103], v[32:47]
	v_mov_b64_e32 v[14:15], s[58:59]
	ds_read_b128 v[48:51], v219 offset:0
	ds_read_b128 v[52:55], v219 offset:0x1000
	ds_read_b128 v[56:59], v220 offset:0
	ds_read_b128 v[60:63], v220 offset:0x1000
	s_nop 0
	s_waitcnt lgkmcnt(0)
	s_nop 0
	v_mfma_f32_32x32x16_bf16 v[16:31], v[48:51], v[104:107], v[16:31]
	v_mfma_f32_32x32x16_bf16 v[32:47], v[52:55], v[104:107], v[32:47]
	v_mfma_f32_32x32x16_bf16 v[16:31], v[56:59], v[108:111], v[16:31]
	v_mfma_f32_32x32x16_bf16 v[32:47], v[60:63], v[108:111], v[32:47]
	s_nop 11
	v_max_f32_e32 v48, v33, v33
	v_max_f32_e32 v49, v17, v17
	v_max_f32_e32 v48, v49, v48
	v_max_f32_e32 v49, v34, v34
	v_max_f32_e32 v50, v18, v18
	v_max_f32_e32 v49, v50, v49
	v_max_f32_e32 v50, v35, v35
	v_max_f32_e32 v51, v19, v19
	v_max3_f32 v48, v16, v32, v48
	v_max_f32_e32 v50, v51, v50
	v_max3_f32 v48, v48, v49, v50
	v_max_f32_e32 v49, v36, v36
	v_max_f32_e32 v50, v20, v20
	v_max_f32_e32 v49, v50, v49
	v_max_f32_e32 v50, v37, v37
	v_max_f32_e32 v51, v21, v21
	v_max_f32_e32 v50, v51, v50
	v_max3_f32 v48, v48, v49, v50
	v_max_f32_e32 v49, v38, v38
	v_max_f32_e32 v50, v22, v22
	v_max_f32_e32 v49, v50, v49
	v_max_f32_e32 v50, v39, v39
	v_max_f32_e32 v51, v23, v23
	v_max_f32_e32 v50, v51, v50
	v_max3_f32 v48, v48, v49, v50
	v_max_f32_e32 v49, v40, v40
	v_max_f32_e32 v50, v24, v24
	v_max_f32_e32 v49, v50, v49
	v_max_f32_e32 v50, v41, v41
	v_max_f32_e32 v51, v25, v25
	v_max_f32_e32 v50, v51, v50
	v_max3_f32 v48, v48, v49, v50
	v_max_f32_e32 v49, v42, v42
	v_max_f32_e32 v50, v26, v26
	v_max_f32_e32 v49, v50, v49
	v_max_f32_e32 v50, v43, v43
	v_max_f32_e32 v51, v27, v27
	v_max_f32_e32 v50, v51, v50
	v_max3_f32 v48, v48, v49, v50
	v_max_f32_e32 v49, v44, v44
	v_max_f32_e32 v50, v28, v28
	v_max_f32_e32 v49, v50, v49
	v_max_f32_e32 v50, v45, v45
	v_max_f32_e32 v51, v29, v29
	v_max_f32_e32 v50, v51, v50
	v_max3_f32 v48, v48, v49, v50
	v_max_f32_e32 v49, v46, v46
	v_max_f32_e32 v50, v30, v30
	v_max_f32_e32 v49, v50, v49
	v_max_f32_e32 v50, v47, v47
	v_max_f32_e32 v51, v31, v31
	v_max_f32_e32 v50, v51, v50
	v_max3_f32 v48, v48, v49, v50
	v_mov_b32_e32 v49, v48
	s_nop 1
	v_permlane32_swap_b32_e32 v48, v49
	v_max_f32_e32 v49, v49, v49
	v_max_f32_e32 v48, v48, v48
	v_max_f32_e32 v49, v48, v49
	v_sub_f32_e32 v16, v16, v49
	v_sub_f32_e32 v32, v32, v49
	v_exp_f32_e32 v16, v16
	v_sub_f32_e32 v17, v17, v49
	v_exp_f32_e32 v32, v32
	v_sub_f32_e32 v33, v33, v49
	v_exp_f32_e32 v17, v17
	v_sub_f32_e32 v18, v18, v49
	v_exp_f32_e32 v33, v33
	v_sub_f32_e32 v34, v34, v49
	v_add_f32_e32 v48, 0, v16
	v_exp_f32_e32 v18, v18
	v_sub_f32_e32 v19, v19, v49
	v_add_f32_e32 v48, v32, v48
	v_exp_f32_e32 v34, v34
	v_sub_f32_e32 v35, v35, v49
	v_add_f32_e32 v48, v17, v48
	v_exp_f32_e32 v19, v19
	v_sub_f32_e32 v20, v20, v49
	v_add_f32_e32 v48, v33, v48
	v_exp_f32_e32 v35, v35
	v_sub_f32_e32 v36, v36, v49
	v_add_f32_e32 v48, v18, v48
	v_exp_f32_e32 v20, v20
	v_sub_f32_e32 v21, v21, v49
	v_add_f32_e32 v48, v34, v48
	v_exp_f32_e32 v36, v36
	v_sub_f32_e32 v37, v37, v49
	v_add_f32_e32 v48, v19, v48
	v_exp_f32_e32 v21, v21
	v_sub_f32_e32 v22, v22, v49
	v_add_f32_e32 v48, v35, v48
	v_exp_f32_e32 v37, v37
	v_sub_f32_e32 v38, v38, v49
	v_add_f32_e32 v48, v20, v48
	v_exp_f32_e32 v22, v22
	v_sub_f32_e32 v23, v23, v49
	v_add_f32_e32 v48, v36, v48
	v_exp_f32_e32 v38, v38
	v_sub_f32_e32 v39, v39, v49
	v_add_f32_e32 v48, v21, v48
	v_exp_f32_e32 v23, v23
	v_sub_f32_e32 v24, v24, v49
	v_add_f32_e32 v48, v37, v48
	v_exp_f32_e32 v39, v39
	v_sub_f32_e32 v40, v40, v49
	v_add_f32_e32 v48, v22, v48
	v_exp_f32_e32 v24, v24
	v_sub_f32_e32 v25, v25, v49
	v_add_f32_e32 v48, v38, v48
	v_exp_f32_e32 v40, v40
	v_sub_f32_e32 v41, v41, v49
	v_add_f32_e32 v48, v23, v48
	v_exp_f32_e32 v25, v25
	v_sub_f32_e32 v26, v26, v49
	v_add_f32_e32 v48, v39, v48
	v_exp_f32_e32 v41, v41
	v_sub_f32_e32 v42, v42, v49
	v_add_f32_e32 v48, v24, v48
	v_exp_f32_e32 v26, v26
	v_sub_f32_e32 v27, v27, v49
	v_add_f32_e32 v48, v40, v48
	v_exp_f32_e32 v42, v42
	v_sub_f32_e32 v43, v43, v49
	v_add_f32_e32 v48, v25, v48
	v_exp_f32_e32 v27, v27
	v_sub_f32_e32 v28, v28, v49
	v_add_f32_e32 v48, v41, v48
	v_exp_f32_e32 v43, v43
	v_sub_f32_e32 v44, v44, v49
	v_add_f32_e32 v48, v26, v48
	v_exp_f32_e32 v28, v28
	v_sub_f32_e32 v29, v29, v49
	v_add_f32_e32 v48, v42, v48
	v_exp_f32_e32 v44, v44
	v_sub_f32_e32 v45, v45, v49
	v_add_f32_e32 v48, v27, v48
	v_exp_f32_e32 v29, v29
	v_sub_f32_e32 v30, v30, v49
	v_add_f32_e32 v48, v43, v48
	v_exp_f32_e32 v45, v45
	v_sub_f32_e32 v46, v46, v49
	v_add_f32_e32 v48, v28, v48
	v_exp_f32_e32 v30, v30
	v_sub_f32_e32 v31, v31, v49
	v_add_f32_e32 v48, v44, v48
	v_exp_f32_e32 v46, v46
	v_sub_f32_e32 v47, v47, v49
	v_add_f32_e32 v48, v29, v48
	v_exp_f32_e32 v31, v31
	v_add_f32_e32 v48, v45, v48
	v_exp_f32_e32 v47, v47
	v_add_f32_e32 v48, v30, v48
	v_add_f32_e32 v48, v46, v48
	v_add_f32_e32 v48, v31, v48
	v_add_f32_e32 v48, v47, v48
	s_waitcnt vmcnt(3) lgkmcnt(0)
	s_barrier
; #define DSR128(dst, addr, off) asm volatile("ds_read_b128 %0, %1 offset:%2" : "=&v"(dst) : "v"(addr), "i"(off))
; template <bool FIRST, bool HAS_PREV> ...
;     ...
;     { const float nm = FIRST ? 0.f : -st.mrun;
; #pragma unroll
;       for (int i = 0; i < 16; ++i) { c0[i] = nm; c1[i] = nm; } }
; #pragma unroll
;     for (int ks = 0; ks < 2; ++ks) { DSR128(kf[2 * ks], ka[ks], 0); DSR128(kf[2 * ks + 1], ka[ks], 4096); }
;     asm volatile("s_waitcnt lgkmcnt(0)" : "+v"(kf[0]), "+v"(kf[1]), "+v"(kf[2]), "+v"(kf[3]));
; #pragma unroll
;     for (int ks = 0; ks < 2; ++ks) {
;         c0 = __builtin_amdgcn_mfma_f32_32x32x16_bf16(kf[2 * ks], qr[ks], c0, 0, 0, 0);
;         c1 = __builtin_amdgcn_mfma_f32_32x32x16_bf16(kf[2 * ks + 1], qr[ks], c1, 0, 0, 0);
;     }
;     __builtin_amdgcn_sched_barrier(0);
;     { bf16x8 kg[4];
; #pragma unroll
;       for (int ks = 0; ks < 2; ++ks) { DSR128(kg[2 * ks], ka[2 + ks], 0); DSR128(kg[2 * ks + 1], ka[2 + ks], 4096); }
;       asm volatile("s_waitcnt lgkmcnt(0)" : "+v"(kg[0]), "+v"(kg[1]), "+v"(kg[2]), "+v"(kg[3]));
; #pragma unroll
;       for (int ks = 0; ks < 2; ++ks) {
;           c0 = __builtin_amdgcn_mfma_f32_32x32x16_bf16(kg[2 * ks], qr[2 + ks], c0, 0, 0, 0);
;           c1 = __builtin_amdgcn_mfma_f32_32x32x16_bf16(kg[2 * ks + 1], qr[2 + ks], c1, 0, 0, 0);
;       } }
;     __builtin_amdgcn_sched_barrier(0);
;     if (HAS_PREV) {
; #pragma unroll
;         for (int e = 0; e < 4; ++e) DSR128(vA[e], va[0], e * 4096);
;     }
;     float mx = fmaxf(c0[0], c1[0]);
; #pragma unroll
;     for (int i = 1; i < 16; ++i) mx = fmaxf(mx, fmaxf(c0[i], c1[i]));
;     mx = swap_max(mx);
;     float a = 1.0f;
;     { const float dl = FIRST ? mx : ((mx > 8.0f) ? mx : 0.f);
;       if (FIRST || __any(dl != 0.f)) {
; #pragma unroll
;           for (int i = 0; i < 16; ++i) { c0[i] -= dl; c1[i] -= dl; }
;           st.mrun += dl; if (!FIRST) a = __builtin_amdgcn_exp2f(-dl);
; __device__ __forceinline__ void attn_unit(LAS unsigned char* lds, const bf16* __restrict__ Qb, const bf16* __restrict__ Kb, const bf16* __restrict__ VT, bf16* __restrict__ Y,
;                                           const float* __restrict__ gsub, float lam, int b, int h, int qb, float* o1scr) {
;     ...
;         ATT_STEP(0, true, false);
; #pragma unroll 1
;         for (int t = 1; t < 32; ++t) ATT_STEP(t, false, true);
	ds_read_b128 v[128:131], v209 offset:8192
	ds_read_b128 v[132:135], v209 offset:12288
	ds_read_b128 v[136:139], v211 offset:8192
	ds_read_b128 v[230:233], v215 offset:8192
	ds_read_b128 v[234:237], v215 offset:12288
	ds_read_b128 v[140:143], v211 offset:12288
	ds_read_b128 v[222:225], v213 offset:8192
	ds_read_b128 v[226:229], v213 offset:12288
	v_pk_add_f32 v[198:199], v[48:49], 0 op_sel_hi:[1,0]
	v_xor_b32_e32 v158, 0x80000000, v49
	v_mov_b32_e32 v159, v158
	v_mov_b32_e32 v160, v158
	v_mov_b32_e32 v161, v158
	v_mov_b32_e32 v162, v158
	v_mov_b32_e32 v163, v158
	v_mov_b32_e32 v164, v158
	v_mov_b32_e32 v165, v158
	v_mov_b32_e32 v166, v158
	v_mov_b32_e32 v167, v158
	v_mov_b32_e32 v168, v158
	v_mov_b32_e32 v169, v158
	v_mov_b32_e32 v170, v158
	v_mov_b32_e32 v171, v158
	v_mov_b32_e32 v172, v158
	v_mov_b32_e32 v173, v158
	v_add_u32_e32 v174, 0x6000, v210
	v_add_u32_e32 v175, 0x6000, v212
	v_add_u32_e32 v178, 0x6000, v214
	v_add_u32_e32 v179, 0x6000, v216
	v_cvt_pk_bf16_f32 v124, v16, v17
	v_cvt_pk_bf16_f32 v125, v18, v19
	v_cvt_pk_bf16_f32 v126, v20, v21
	v_cvt_pk_bf16_f32 v127, v22, v23
	v_cvt_pk_bf16_f32 v120, v24, v25
	v_cvt_pk_bf16_f32 v121, v26, v27
	v_cvt_pk_bf16_f32 v122, v28, v29
	v_cvt_pk_bf16_f32 v123, v30, v31
	v_cvt_pk_bf16_f32 v116, v32, v33
	v_cvt_pk_bf16_f32 v117, v34, v35
	v_cvt_pk_bf16_f32 v118, v36, v37
	v_cvt_pk_bf16_f32 v119, v38, v39
	v_cvt_pk_bf16_f32 v112, v40, v41
	v_cvt_pk_bf16_f32 v113, v42, v43
	v_cvt_pk_bf16_f32 v114, v44, v45
	v_cvt_pk_bf16_f32 v115, v46, v47
	v_mov_b64_e32 v[30:31], v[14:15]
	v_mov_b64_e32 v[46:47], v[14:15]
	v_mov_b64_e32 v[62:63], v[14:15]
	v_lshl_add_u64 v[200:201], v[194:195], 0, s[82:83]
	v_subrev_u32_e32 v193, s36, v194
	s_add_u32 s54, s36, s82
	s_addc_u32 s55, s37, s83
	v_subrev_u32_e32 v182, s30, v196
	s_mov_b32 s56, s30
	s_mov_b32 s57, s31
	v_add_u32_e32 v182, 0x23008000, v182
	v_add_u32_e32 v183, 0x2000, v182
	s_mov_b32 s44, 0
	s_mov_b32 s52, 2
	s_mov_b64 s[46:47], 0
	v_mov_b64_e32 v[28:29], v[12:13]
	v_mov_b64_e32 v[26:27], v[10:11]
	v_mov_b64_e32 v[24:25], v[8:9]
	v_mov_b64_e32 v[22:23], v[6:7]
	v_mov_b64_e32 v[20:21], v[4:5]
	v_mov_b64_e32 v[18:19], v[2:3]
	v_mov_b64_e32 v[16:17], v[0:1]
	v_mov_b64_e32 v[44:45], v[12:13]
	v_mov_b64_e32 v[42:43], v[10:11]
	v_mov_b64_e32 v[40:41], v[8:9]
	v_mov_b64_e32 v[38:39], v[6:7]
	v_mov_b64_e32 v[36:37], v[4:5]
	v_mov_b64_e32 v[34:35], v[2:3]
	v_mov_b64_e32 v[32:33], v[0:1]
	s_mov_b32 s53, 1
	v_mov_b64_e32 v[60:61], v[12:13]
	v_mov_b64_e32 v[58:59], v[10:11]
	v_mov_b64_e32 v[56:57], v[8:9]
	v_mov_b64_e32 v[54:55], v[6:7]
	v_mov_b64_e32 v[52:53], v[4:5]
	v_mov_b64_e32 v[50:51], v[2:3]
	v_mov_b64_e32 v[48:49], v[0:1]
.LBB0_561:
	s_mov_b32 s51, 0
	s_waitcnt lgkmcnt(3)
	v_mfma_f32_32x32x16_bf16 v[80:95], v[128:131], v[96:99], v[158:173]
	v_mfma_f32_32x32x16_bf16 v[64:79], v[132:135], v[96:99], v[158:173]
	v_mfma_f32_32x32x16_bf16 v[80:95], v[136:139], v[100:103], v[80:95]
	s_waitcnt lgkmcnt(0)
	v_mfma_f32_32x32x16_bf16 v[64:79], v[140:143], v[100:103], v[64:79]
	s_waitcnt lgkmcnt(0)
	v_mfma_f32_32x32x16_bf16 v[80:95], v[222:225], v[104:107], v[80:95]
	v_mfma_f32_32x32x16_bf16 v[64:79], v[226:229], v[104:107], v[64:79]
	v_mfma_f32_32x32x16_bf16 v[80:95], v[230:233], v[108:111], v[80:95]
	v_mfma_f32_32x32x16_bf16 v[64:79], v[234:237], v[108:111], v[64:79]
	ds_read_b128 v[140:143], v174 offset:0
	ds_read_b128 v[136:139], v174 offset:4096
	ds_read_b128 v[132:135], v174 offset:8192
	ds_read_b128 v[128:131], v174 offset:12288
	s_nop 6
	v_max3_f32 v202, v80, v81, v82
	v_max3_f32 v202, v202, v83, v84
	v_max3_f32 v202, v202, v85, v86
	v_max3_f32 v202, v202, v87, v88
	v_max3_f32 v202, v202, v89, v90
	v_max3_f32 v202, v202, v91, v92
	v_max3_f32 v202, v202, v93, v94
	v_max3_f32 v204, v64, v65, v66
	v_max3_f32 v204, v204, v67, v68
	v_max3_f32 v204, v204, v69, v70
	v_max3_f32 v204, v204, v71, v72
	v_max3_f32 v204, v204, v73, v74
	v_max3_f32 v204, v204, v75, v76
	v_max3_f32 v204, v204, v77, v78
	v_max3_f32 v202, v202, v95, v79
	v_max_f32_e32 v202, v202, v204
	v_mov_b32_e32 v204, v202
	s_nop 1
	v_permlane32_swap_b32_e32 v202, v204
	v_max_f32_e32 v202, v202, v204
	v_cmp_lt_f32_e32 vcc, s84, v202
	s_cbranch_vccnz .Lu3_rare_1

; #define DSR128(dst, addr, off) asm volatile("ds_read_b128 %0, %1 offset:%2" : "=&v"(dst) : "v"(addr), "i"(off))
; #define ATT_EXPS(E) do { _Pragma("unroll") for (int j = 0; j < 8; ++j) { const int i = (E) * 8 + j; \
;         if (i < 16) { c0[i] = __builtin_amdgcn_exp2f(c0[i]); ps += c0[i]; } else { c1[i - 16] = __builtin_amdgcn_exp2f(c1[i - 16]); ps += c1[i - 16]; } } \
;         asm volatile("" : "+v"(c0), "+v"(c1), "+v"(ps)); __builtin_amdgcn_sched_barrier(0); } while (0)
; #define ATT_PV(KK, VF) do { _Pragma("unroll") for (int e = 0; e < 4; ++e) o[e] = __builtin_amdgcn_mfma_f32_32x32x16_bf16(VF[e], pbp[KK], o[e], 0, 0, 0); } while (0)
; #define ATT_TIE(N, VF) asm volatile("s_waitcnt lgkmcnt(" #N ")" : "+v"(VF[0]), "+v"(VF[1]), "+v"(VF[2]), "+v"(VF[3]))
; template <bool FIRST, bool HAS_PREV> ...
;     ...
;         for (int e = 0; e < 4; ++e) DSR128(vA[e], va[2], e * 4096);
;         ATT_TIE(4, vB); ATT_PV(1, vB); ATT_EXPS(1);
; #pragma unroll
;         for (int e = 0; e < 4; ++e) DSR128(vB[e], va[3], e * 4096);
;         ATT_TIE(4, vA); ATT_PV(2, vA); ATT_EXPS(2);
;         ATT_TIE(0, vB); ATT_PV(3, vB); ATT_EXPS(3);
.Lu3_nov_1:
	ds_read_b128 v[120:123], v179 offset:0
	ds_read_b128 v[140:143], v179 offset:4096
	ds_read_b128 v[222:225], v179 offset:8192
	ds_read_b128 v[226:229], v179 offset:12288
	s_waitcnt lgkmcnt(4)
	v_exp_f32_e32 v66, v66
	v_exp_f32_e32 v67, v67
	v_add_f32_e32 v192, v95, v192
	v_add_f32_e32 v192, v64, v192
	v_mfma_f32_32x32x16_bf16 v[48:63], v[124:127], v[116:119], v[48:63]
	v_exp_f32_e32 v68, v68
	v_exp_f32_e32 v69, v69
	v_add_f32_e32 v192, v65, v192
	v_add_f32_e32 v192, v66, v192
	v_mfma_f32_32x32x16_bf16 v[32:47], v[128:131], v[116:119], v[32:47]
	v_exp_f32_e32 v70, v70
	v_exp_f32_e32 v71, v71
	v_add_f32_e32 v192, v67, v192
	v_add_f32_e32 v192, v68, v192
	v_mfma_f32_32x32x16_bf16 v[16:31], v[132:135], v[116:119], v[16:31]
	v_exp_f32_e32 v72, v72
	v_exp_f32_e32 v73, v73
	v_add_f32_e32 v192, v69, v192
	v_add_f32_e32 v192, v70, v192
	v_mfma_f32_32x32x16_bf16 v[0:15], v[136:139], v[116:119], v[0:15]
	s_cmp_gt_u32 s53, 29
	s_cbranch_scc1 .Lu3_w0_1
	s_waitcnt vmcnt(3) lgkmcnt(0)
	s_branch .Lu3_wd_1

; template <bool FIRST, bool HAS_PREV> ...
;     ...
;     { const float nm = FIRST ? 0.f : -st.mrun;
; #pragma unroll
;       for (int i = 0; i < 16; ++i) { c0[i] = nm; c1[i] = nm; } }
; #pragma unroll
;     for (int ks = 0; ks < 2; ++ks) { DSR128(kf[2 * ks], ka[ks], 0); DSR128(kf[2 * ks + 1], ka[ks], 4096); }
;     asm volatile("s_waitcnt lgkmcnt(0)" : "+v"(kf[0]), "+v"(kf[1]), "+v"(kf[2]), "+v"(kf[3]));
; #pragma unroll
;     for (int ks = 0; ks < 2; ++ks) {
;         c0 = __builtin_amdgcn_mfma_f32_32x32x16_bf16(kf[2 * ks], qr[ks], c0, 0, 0, 0);
;         c1 = __builtin_amdgcn_mfma_f32_32x32x16_bf16(kf[2 * ks + 1], qr[ks], c1, 0, 0, 0);
;     }
;     __builtin_amdgcn_sched_barrier(0);
;     { bf16x8 kg[4];
; #pragma unroll
;       for (int ks = 0; ks < 2; ++ks) { DSR128(kg[2 * ks], ka[2 + ks], 0); DSR128(kg[2 * ks + 1], ka[2 + ks], 4096); }
;       asm volatile("s_waitcnt lgkmcnt(0)" : "+v"(kg[0]), "+v"(kg[1]), "+v"(kg[2]), "+v"(kg[3]));
; #pragma unroll
;       for (int ks = 0; ks < 2; ++ks) {
;     ...
;         ATT_TIE(4, vA); ATT_PV(2, vA); ATT_EXPS(2);
;         ATT_TIE(0, vB); ATT_PV(3, vB); ATT_EXPS(3);
;     } else {
; #pragma unroll
;         for (int i = 0; i < 16; ++i) { c0[i] = __builtin_amdgcn_exp2f(c0[i]); ps += c0[i]; c1[i] = __builtin_amdgcn_exp2f(c1[i]); ps += c1[i]; }
;     }
;     ...
;     st.l = st.l * a + ps;
;     if (!FIRST) { if (__any(a != 1.0f)) {
; #pragma unroll
;         for (int e = 0; e < 4; ++e)
; #pragma unroll
;             for (int i = 0; i < 16; ++i) o[e][i] *= a; } }
;     { u32x4 w;
;       w.x = pg8::cvt_pk_bf16(c0[0], c0[1]); w.y = pg8::cvt_pk_bf16(c0[2], c0[3]); w.z = pg8::cvt_pk_bf16(c0[4], c0[5]); w.w = pg8::cvt_pk_bf16(c0[6], c0[7]); pbp[0] = __builtin_bit_cast(bf16x8, w);
;       w.x = pg8::cvt_pk_bf16(c0[8], c0[9]); w.y = pg8::cvt_pk_bf16(c0[10], c0[11]); w.z = pg8::cvt_pk_bf16(c0[12], c0[13]); w.w = pg8::cvt_pk_bf16(c0[14], c0[15]); pbp[1] = __builtin_bit_cast(bf16x8, w);
;       w.x = pg8::cvt_pk_bf16(c1[0], c1[1]); w.y = pg8::cvt_pk_bf16(c1[2], c1[3]); w.z = pg8::cvt_pk_bf16(c1[4], c1[5]); w.w = pg8::cvt_pk_bf16(c1[6], c1[7]); pbp[2] = __builtin_bit_cast(bf16x8, w);
;       w.x = pg8::cvt_pk_bf16(c1[8], c1[9]); w.y = pg8::cvt_pk_bf16(c1[10], c1[11]); w.z = pg8::cvt_pk_bf16(c1[12], c1[13]); w.w = pg8::cvt_pk_bf16(c1[14], c1[15]); pbp[3] = __builtin_bit_cast(bf16x8, w); }
; }
.Lu3_wd_1:
	s_barrier
	s_cmp_eq_u32 s46, 0x78000
	s_cbranch_scc1 .Lu3_skipk_1
	ds_read_b128 v[128:131], v209 offset:16384
	ds_read_b128 v[132:135], v209 offset:20480
	ds_read_b128 v[136:139], v211 offset:16384
	ds_read_b128 v[230:233], v215 offset:16384
	ds_read_b128 v[234:237], v215 offset:20480
.Lu3_skipk_1:
	v_exp_f32_e32 v74, v74
	v_exp_f32_e32 v75, v75
	v_add_f32_e32 v192, v71, v192
	v_add_f32_e32 v192, v72, v192
	v_mfma_f32_32x32x16_bf16 v[48:63], v[120:123], v[112:115], v[48:63]
	v_exp_f32_e32 v76, v76
	v_exp_f32_e32 v77, v77
	v_add_f32_e32 v192, v73, v192
	v_add_f32_e32 v192, v74, v192
	v_add_f32_e32 v192, v75, v192
	v_mfma_f32_32x32x16_bf16 v[32:47], v[140:143], v[112:115], v[32:47]
	v_exp_f32_e32 v78, v78
	v_exp_f32_e32 v79, v79
	v_add_f32_e32 v192, v76, v192
	v_add_f32_e32 v192, v77, v192
	v_mfma_f32_32x32x16_bf16 v[16:31], v[222:225], v[112:115], v[16:31]
	v_mfma_f32_32x32x16_bf16 v[0:15], v[226:229], v[112:115], v[0:15]
	v_add_f32_e32 v192, v78, v192
	v_add_f32_e32 v192, v79, v192
	s_cmp_lg_u32 s51, 0
	s_cbranch_scc1 .Lu3_resc_1
	v_add_f32_e32 v198, v198, v192
.Lu3_e_1:
	s_add_u32 s46, s46, 0x4000
	s_addc_u32 s47, s47, 0
	s_add_i32 s53, s53, 1
	s_add_u32 s54, s54, 0x10000
	s_addc_u32 s55, s55, 0
	s_add_u32 s56, s56, 0x4000
	s_addc_u32 s57, s57, 0
	s_cmp_eq_u32 s46, 0x7c000
	s_cbranch_scc1 .Lu3_exit
	ds_read_b128 v[140:143], v211 offset:20480
	ds_read_b128 v[222:225], v213 offset:16384
	ds_read_b128 v[226:229], v213 offset:20480
	v_cvt_pk_bf16_f32 v124, v80, v81
	v_cvt_pk_bf16_f32 v125, v82, v83
	v_cvt_pk_bf16_f32 v126, v84, v85
	v_cvt_pk_bf16_f32 v127, v86, v87
	v_cvt_pk_bf16_f32 v120, v88, v89
	v_cvt_pk_bf16_f32 v121, v90, v91
	v_cvt_pk_bf16_f32 v122, v92, v93
	v_cvt_pk_bf16_f32 v123, v94, v95
	v_cvt_pk_bf16_f32 v116, v64, v65
	v_cvt_pk_bf16_f32 v117, v66, v67
	v_cvt_pk_bf16_f32 v118, v68, v69
	v_cvt_pk_bf16_f32 v119, v70, v71
	v_cvt_pk_bf16_f32 v112, v72, v73
	v_cvt_pk_bf16_f32 v113, v74, v75
	v_cvt_pk_bf16_f32 v114, v76, v77
	v_cvt_pk_bf16_f32 v115, v78, v79
	s_mov_b32 s51, 0
	s_waitcnt lgkmcnt(3)
	v_mfma_f32_32x32x16_bf16 v[80:95], v[128:131], v[96:99], v[158:173]
	v_mfma_f32_32x32x16_bf16 v[64:79], v[132:135], v[96:99], v[158:173]
	v_mfma_f32_32x32x16_bf16 v[80:95], v[136:139], v[100:103], v[80:95]
	s_waitcnt lgkmcnt(0)
	v_mfma_f32_32x32x16_bf16 v[64:79], v[140:143], v[100:103], v[64:79]
	s_waitcnt lgkmcnt(0)
	v_mfma_f32_32x32x16_bf16 v[80:95], v[222:225], v[104:107], v[80:95]
	v_mfma_f32_32x32x16_bf16 v[64:79], v[226:229], v[104:107], v[64:79]
	v_mfma_f32_32x32x16_bf16 v[80:95], v[230:233], v[108:111], v[80:95]
	v_mfma_f32_32x32x16_bf16 v[64:79], v[234:237], v[108:111], v[64:79]
	ds_read_b128 v[140:143], v174 offset:16384
	ds_read_b128 v[136:139], v174 offset:20480
	ds_read_b128 v[132:135], v174 offset:24576
	ds_read_b128 v[128:131], v174 offset:28672
	s_nop 6
	v_max3_f32 v202, v80, v81, v82
	v_max3_f32 v202, v202, v83, v84
	v_max3_f32 v202, v202, v85, v86
	v_max3_f32 v202, v202, v87, v88
	v_max3_f32 v202, v202, v89, v90
	v_max3_f32 v202, v202, v91, v92
	v_max3_f32 v202, v202, v93, v94
	v_max3_f32 v204, v64, v65, v66
	v_max3_f32 v204, v204, v67, v68
	v_max3_f32 v204, v204, v69, v70
	v_max3_f32 v204, v204, v71, v72
	v_max3_f32 v204, v204, v73, v74
	v_max3_f32 v204, v204, v75, v76
	v_max3_f32 v204, v204, v77, v78
	v_max3_f32 v202, v202, v95, v79
	v_max_f32_e32 v202, v202, v204
	v_mov_b32_e32 v204, v202
	s_nop 1
	v_permlane32_swap_b32_e32 v202, v204
	v_max_f32_e32 v202, v202, v204
	v_cmp_lt_f32_e32 vcc, s84, v202
	s_cbranch_vccnz .Lu3_rare_2

; #define DSR128(dst, addr, off) asm volatile("ds_read_b128 %0, %1 offset:%2" : "=&v"(dst) : "v"(addr), "i"(off))
; #define ATT_EXPS(E) do { _Pragma("unroll") for (int j = 0; j < 8; ++j) { const int i = (E) * 8 + j; \
;         if (i < 16) { c0[i] = __builtin_amdgcn_exp2f(c0[i]); ps += c0[i]; } else { c1[i - 16] = __builtin_amdgcn_exp2f(c1[i - 16]); ps += c1[i - 16]; } } \
;         asm volatile("" : "+v"(c0), "+v"(c1), "+v"(ps)); __builtin_amdgcn_sched_barrier(0); } while (0)
; #define ATT_PV(KK, VF) do { _Pragma("unroll") for (int e = 0; e < 4; ++e) o[e] = __builtin_amdgcn_mfma_f32_32x32x16_bf16(VF[e], pbp[KK], o[e], 0, 0, 0); } while (0)
; #define ATT_TIE(N, VF) asm volatile("s_waitcnt lgkmcnt(" #N ")" : "+v"(VF[0]), "+v"(VF[1]), "+v"(VF[2]), "+v"(VF[3]))
; template <bool FIRST, bool HAS_PREV> ...
;     ...
;         for (int e = 0; e < 4; ++e) DSR128(vA[e], va[2], e * 4096);
;         ATT_TIE(4, vB); ATT_PV(1, vB); ATT_EXPS(1);
; #pragma unroll
;         for (int e = 0; e < 4; ++e) DSR128(vB[e], va[3], e * 4096);
;         ATT_TIE(4, vA); ATT_PV(2, vA); ATT_EXPS(2);
;         ATT_TIE(0, vB); ATT_PV(3, vB); ATT_EXPS(3);
.Lu3_nov_2:
	ds_read_b128 v[120:123], v179 offset:16384
	ds_read_b128 v[140:143], v179 offset:20480
	ds_read_b128 v[222:225], v179 offset:24576
	ds_read_b128 v[226:229], v179 offset:28672
	s_waitcnt lgkmcnt(4)
	v_exp_f32_e32 v66, v66
	v_exp_f32_e32 v67, v67
	v_add_f32_e32 v192, v95, v192
	v_add_f32_e32 v192, v64, v192
	v_mfma_f32_32x32x16_bf16 v[48:63], v[124:127], v[116:119], v[48:63]
	v_exp_f32_e32 v68, v68
	v_exp_f32_e32 v69, v69
	v_add_f32_e32 v192, v65, v192
	v_add_f32_e32 v192, v66, v192
	v_mfma_f32_32x32x16_bf16 v[32:47], v[128:131], v[116:119], v[32:47]
	v_exp_f32_e32 v70, v70
	v_exp_f32_e32 v71, v71
	v_add_f32_e32 v192, v67, v192
	v_add_f32_e32 v192, v68, v192
	v_mfma_f32_32x32x16_bf16 v[16:31], v[132:135], v[116:119], v[16:31]
	v_exp_f32_e32 v72, v72
	v_exp_f32_e32 v73, v73
	v_add_f32_e32 v192, v69, v192
	v_add_f32_e32 v192, v70, v192
	v_mfma_f32_32x32x16_bf16 v[0:15], v[136:139], v[116:119], v[0:15]
	s_cmp_gt_u32 s53, 29
	s_cbranch_scc1 .Lu3_w0_2
	s_waitcnt vmcnt(3) lgkmcnt(0)
	s_branch .Lu3_wd_2

; #define DSR128(dst, addr, off) asm volatile("ds_read_b128 %0, %1 offset:%2" : "=&v"(dst) : "v"(addr), "i"(off))
; template <bool FIRST, bool HAS_PREV> ...
;     ...
;     for (int ks = 0; ks < 2; ++ks) { DSR128(kf[2 * ks], ka[ks], 0); DSR128(kf[2 * ks + 1], ka[ks], 4096); }
;     ...
;       for (int ks = 0; ks < 2; ++ks) { DSR128(kg[2 * ks], ka[2 + ks], 0); DSR128(kg[2 * ks + 1], ka[2 + ks], 4096); }
.Lu3_wd_2:
	s_barrier
	ds_read_b128 v[128:131], v209 offset:0
	ds_read_b128 v[132:135], v209 offset:4096
	ds_read_b128 v[136:139], v211 offset:0
	ds_read_b128 v[230:233], v215 offset:0
	ds_read_b128 v[234:237], v215 offset:4096

; #define DSR128(dst, addr, off) asm volatile("ds_read_b128 %0, %1 offset:%2" : "=&v"(dst) : "v"(addr), "i"(off))
; template <bool FIRST, bool HAS_PREV> ...
;     ...
;     { const float nm = FIRST ? 0.f : -st.mrun;
; #pragma unroll
;       for (int i = 0; i < 16; ++i) { c0[i] = nm; c1[i] = nm; } }
; #pragma unroll
;     for (int ks = 0; ks < 2; ++ks) { DSR128(kf[2 * ks], ka[ks], 0); DSR128(kf[2 * ks + 1], ka[ks], 4096); }
;     asm volatile("s_waitcnt lgkmcnt(0)" : "+v"(kf[0]), "+v"(kf[1]), "+v"(kf[2]), "+v"(kf[3]));
; #pragma unroll
;     for (int ks = 0; ks < 2; ++ks) {
;         c0 = __builtin_amdgcn_mfma_f32_32x32x16_bf16(kf[2 * ks], qr[ks], c0, 0, 0, 0);
;         c1 = __builtin_amdgcn_mfma_f32_32x32x16_bf16(kf[2 * ks + 1], qr[ks], c1, 0, 0, 0);
;     }
;     __builtin_amdgcn_sched_barrier(0);
;     { bf16x8 kg[4];
; #pragma unroll
;       for (int ks = 0; ks < 2; ++ks) { DSR128(kg[2 * ks], ka[2 + ks], 0); DSR128(kg[2 * ks + 1], ka[2 + ks], 4096); }
;       asm volatile("s_waitcnt lgkmcnt(0)" : "+v"(kg[0]), "+v"(kg[1]), "+v"(kg[2]), "+v"(kg[3]));
; #pragma unroll
;       for (int ks = 0; ks < 2; ++ks) {
;           c0 = __builtin_amdgcn_mfma_f32_32x32x16_bf16(kg[2 * ks], qr[2 + ks], c0, 0, 0, 0);
;           c1 = __builtin_amdgcn_mfma_f32_32x32x16_bf16(kg[2 * ks + 1], qr[2 + ks], c1, 0, 0, 0);
;       } }
;     __builtin_amdgcn_sched_barrier(0);
;     if (HAS_PREV) {
; #pragma unroll
;         for (int e = 0; e < 4; ++e) DSR128(vA[e], va[0], e * 4096);
;     }
;     float mx = fmaxf(c0[0], c1[0]);
; #pragma unroll
;     for (int i = 1; i < 16; ++i) mx = fmaxf(mx, fmaxf(c0[i], c1[i]));
;     mx = swap_max(mx);
;     float a = 1.0f;
;     { const float dl = FIRST ? mx : ((mx > 8.0f) ? mx : 0.f);
;       if (FIRST || __any(dl != 0.f)) {
; #pragma unroll
;           for (int i = 0; i < 16; ++i) { c0[i] -= dl; c1[i] -= dl; }
;           st.mrun += dl; if (!FIRST) a = __builtin_amdgcn_exp2f(-dl);
;     ...
;     { u32x4 w;
;       w.x = pg8::cvt_pk_bf16(c0[0], c0[1]); w.y = pg8::cvt_pk_bf16(c0[2], c0[3]); w.z = pg8::cvt_pk_bf16(c0[4], c0[5]); w.w = pg8::cvt_pk_bf16(c0[6], c0[7]); pbp[0] = __builtin_bit_cast(bf16x8, w);
;       w.x = pg8::cvt_pk_bf16(c0[8], c0[9]); w.y = pg8::cvt_pk_bf16(c0[10], c0[11]); w.z = pg8::cvt_pk_bf16(c0[12], c0[13]); w.w = pg8::cvt_pk_bf16(c0[14], c0[15]); pbp[1] = __builtin_bit_cast(bf16x8, w);
.Lu3_e_2:
	s_add_u32 s46, s46, 0x4000
	s_addc_u32 s47, s47, 0
	s_add_i32 s53, s53, 1
	s_add_u32 s54, s54, 0x10000
	s_addc_u32 s55, s55, 0
	s_add_u32 s56, s56, 0x4000
	s_addc_u32 s57, s57, 0
	ds_read_b128 v[140:143], v211 offset:4096
	ds_read_b128 v[222:225], v213 offset:0
	ds_read_b128 v[226:229], v213 offset:4096
	v_cvt_pk_bf16_f32 v124, v80, v81
	v_cvt_pk_bf16_f32 v125, v82, v83
	v_cvt_pk_bf16_f32 v126, v84, v85
	v_cvt_pk_bf16_f32 v127, v86, v87
	v_cvt_pk_bf16_f32 v120, v88, v89
	v_cvt_pk_bf16_f32 v121, v90, v91
	v_cvt_pk_bf16_f32 v122, v92, v93
	v_cvt_pk_bf16_f32 v123, v94, v95
	v_cvt_pk_bf16_f32 v116, v64, v65
	v_cvt_pk_bf16_f32 v117, v66, v67
	v_cvt_pk_bf16_f32 v118, v68, v69
	v_cvt_pk_bf16_f32 v119, v70, v71
	v_cvt_pk_bf16_f32 v112, v72, v73
	v_cvt_pk_bf16_f32 v113, v74, v75
	v_cvt_pk_bf16_f32 v114, v76, v77
	v_cvt_pk_bf16_f32 v115, v78, v79
	s_mov_b32 s51, 0
	s_waitcnt lgkmcnt(3)
	v_mfma_f32_32x32x16_bf16 v[80:95], v[128:131], v[96:99], v[158:173]
	v_mfma_f32_32x32x16_bf16 v[64:79], v[132:135], v[96:99], v[158:173]
	v_mfma_f32_32x32x16_bf16 v[80:95], v[136:139], v[100:103], v[80:95]
	s_waitcnt lgkmcnt(0)
	v_mfma_f32_32x32x16_bf16 v[64:79], v[140:143], v[100:103], v[64:79]
	s_waitcnt lgkmcnt(0)
	v_mfma_f32_32x32x16_bf16 v[80:95], v[222:225], v[104:107], v[80:95]
	v_mfma_f32_32x32x16_bf16 v[64:79], v[226:229], v[104:107], v[64:79]
	v_mfma_f32_32x32x16_bf16 v[80:95], v[230:233], v[108:111], v[80:95]
	v_mfma_f32_32x32x16_bf16 v[64:79], v[234:237], v[108:111], v[64:79]
	ds_read_b128 v[140:143], v174 offset:32768
	ds_read_b128 v[136:139], v174 offset:36864
	ds_read_b128 v[132:135], v174 offset:40960
	ds_read_b128 v[128:131], v174 offset:45056
	s_nop 6
	v_max3_f32 v202, v80, v81, v82
	v_max3_f32 v202, v202, v83, v84
	v_max3_f32 v202, v202, v85, v86
	v_max3_f32 v202, v202, v87, v88
	v_max3_f32 v202, v202, v89, v90
	v_max3_f32 v202, v202, v91, v92
	v_max3_f32 v202, v202, v93, v94
	v_max3_f32 v204, v64, v65, v66
	v_max3_f32 v204, v204, v67, v68
	v_max3_f32 v204, v204, v69, v70
	v_max3_f32 v204, v204, v71, v72
	v_max3_f32 v204, v204, v73, v74
	v_max3_f32 v204, v204, v75, v76
	v_max3_f32 v204, v204, v77, v78
	v_max3_f32 v202, v202, v95, v79
	v_max_f32_e32 v202, v202, v204
	v_mov_b32_e32 v204, v202
	s_nop 1
	v_permlane32_swap_b32_e32 v202, v204
	v_max_f32_e32 v202, v202, v204
	v_cmp_lt_f32_e32 vcc, s84, v202
	s_cbranch_vccnz .Lu3_rare_0

; #define DSR128(dst, addr, off) asm volatile("ds_read_b128 %0, %1 offset:%2" : "=&v"(dst) : "v"(addr), "i"(off))
; #define ATT_EXPS(E) do { _Pragma("unroll") for (int j = 0; j < 8; ++j) { const int i = (E) * 8 + j; \
;         if (i < 16) { c0[i] = __builtin_amdgcn_exp2f(c0[i]); ps += c0[i]; } else { c1[i - 16] = __builtin_amdgcn_exp2f(c1[i - 16]); ps += c1[i - 16]; } } \
;         asm volatile("" : "+v"(c0), "+v"(c1), "+v"(ps)); __builtin_amdgcn_sched_barrier(0); } while (0)
; #define ATT_PV(KK, VF) do { _Pragma("unroll") for (int e = 0; e < 4; ++e) o[e] = __builtin_amdgcn_mfma_f32_32x32x16_bf16(VF[e], pbp[KK], o[e], 0, 0, 0); } while (0)
; #define ATT_TIE(N, VF) asm volatile("s_waitcnt lgkmcnt(" #N ")" : "+v"(VF[0]), "+v"(VF[1]), "+v"(VF[2]), "+v"(VF[3]))
; template <bool FIRST, bool HAS_PREV> ...
;     ...
;         for (int e = 0; e < 4; ++e) DSR128(vA[e], va[2], e * 4096);
;         ATT_TIE(4, vB); ATT_PV(1, vB); ATT_EXPS(1);
; #pragma unroll
;         for (int e = 0; e < 4; ++e) DSR128(vB[e], va[3], e * 4096);
;         ATT_TIE(4, vA); ATT_PV(2, vA); ATT_EXPS(2);
;         ATT_TIE(0, vB); ATT_PV(3, vB); ATT_EXPS(3);
.Lu3_nov_0:
	ds_read_b128 v[120:123], v179 offset:32768
	ds_read_b128 v[140:143], v179 offset:36864
	ds_read_b128 v[222:225], v179 offset:40960
	ds_read_b128 v[226:229], v179 offset:45056
	s_waitcnt lgkmcnt(4)
	v_exp_f32_e32 v66, v66
	v_exp_f32_e32 v67, v67
	v_add_f32_e32 v192, v95, v192
	v_add_f32_e32 v192, v64, v192
	v_mfma_f32_32x32x16_bf16 v[48:63], v[124:127], v[116:119], v[48:63]
	v_exp_f32_e32 v68, v68
	v_exp_f32_e32 v69, v69
	v_add_f32_e32 v192, v65, v192
	v_add_f32_e32 v192, v66, v192
	v_mfma_f32_32x32x16_bf16 v[32:47], v[128:131], v[116:119], v[32:47]
	v_exp_f32_e32 v70, v70
	v_exp_f32_e32 v71, v71
	v_add_f32_e32 v192, v67, v192
	v_add_f32_e32 v192, v68, v192
	v_mfma_f32_32x32x16_bf16 v[16:31], v[132:135], v[116:119], v[16:31]
	v_exp_f32_e32 v72, v72
	v_exp_f32_e32 v73, v73
	v_add_f32_e32 v192, v69, v192
	v_add_f32_e32 v192, v70, v192
	v_mfma_f32_32x32x16_bf16 v[0:15], v[136:139], v[116:119], v[0:15]
	s_cmp_gt_u32 s53, 29
	s_cbranch_scc1 .Lu3_w0_0
	s_waitcnt vmcnt(3) lgkmcnt(0)
	s_branch .Lu3_wd_0

; #define DSR128(dst, addr, off) asm volatile("ds_read_b128 %0, %1 offset:%2" : "=&v"(dst) : "v"(addr), "i"(off))
; template <bool FIRST, bool HAS_PREV> ...
;     ...
;     for (int ks = 0; ks < 2; ++ks) { DSR128(kf[2 * ks], ka[ks], 0); DSR128(kf[2 * ks + 1], ka[ks], 4096); }
;     ...
;       for (int ks = 0; ks < 2; ++ks) { DSR128(kg[2 * ks], ka[2 + ks], 0); DSR128(kg[2 * ks + 1], ka[2 + ks], 4096); }
.Lu3_wd_0:
	s_barrier
	ds_read_b128 v[128:131], v209 offset:8192
	ds_read_b128 v[132:135], v209 offset:12288
	ds_read_b128 v[136:139], v211 offset:8192
	ds_read_b128 v[230:233], v215 offset:8192
	ds_read_b128 v[234:237], v215 offset:12288

; __device__ __forceinline__ unsigned cvt_pk_bf16(float lo, float hi) { cvt_f32x2_t v = {lo, hi}; cvt_bf16x2_t b = __builtin_convertvector(v, cvt_bf16x2_t); return __builtin_bit_cast(unsigned, b); }
; template <bool FIRST, bool HAS_PREV> ...
;     ...
;     { u32x4 w;
;       w.x = pg8::cvt_pk_bf16(c0[0], c0[1]); w.y = pg8::cvt_pk_bf16(c0[2], c0[3]); w.z = pg8::cvt_pk_bf16(c0[4], c0[5]); w.w = pg8::cvt_pk_bf16(c0[6], c0[7]); pbp[0] = __builtin_bit_cast(bf16x8, w);
;       w.x = pg8::cvt_pk_bf16(c0[8], c0[9]); w.y = pg8::cvt_pk_bf16(c0[10], c0[11]); w.z = pg8::cvt_pk_bf16(c0[12], c0[13]); w.w = pg8::cvt_pk_bf16(c0[14], c0[15]); pbp[1] = __builtin_bit_cast(bf16x8, w);
;       w.x = pg8::cvt_pk_bf16(c1[0], c1[1]); w.y = pg8::cvt_pk_bf16(c1[2], c1[3]); w.z = pg8::cvt_pk_bf16(c1[4], c1[5]); w.w = pg8::cvt_pk_bf16(c1[6], c1[7]); pbp[2] = __builtin_bit_cast(bf16x8, w);
;       w.x = pg8::cvt_pk_bf16(c1[8], c1[9]); w.y = pg8::cvt_pk_bf16(c1[10], c1[11]); w.z = pg8::cvt_pk_bf16(c1[12], c1[13]); w.w = pg8::cvt_pk_bf16(c1[14], c1[15]); pbp[3] = __builtin_bit_cast(bf16x8, w); }
; __device__ __forceinline__ void attn_unit(LAS unsigned char* lds, const bf16* __restrict__ Qb, const bf16* __restrict__ Kb, const bf16* __restrict__ VT, bf16* __restrict__ Y,
;                                           const float* __restrict__ gsub, float lam, int b, int h, int qb, float* o1scr) {
;     ...
;         ATT_STEP(0, true, false);
; #pragma unroll 1
;         for (int t = 1; t < 32; ++t) ATT_STEP(t, false, true);
.Lu3_e_0:
	s_add_u32 s46, s46, 0x4000
	s_addc_u32 s47, s47, 0
	s_add_i32 s53, s53, 1
	s_add_u32 s54, s54, 0x10000
	s_addc_u32 s55, s55, 0
	s_add_u32 s56, s56, 0x4000
	s_addc_u32 s57, s57, 0
	ds_read_b128 v[140:143], v211 offset:12288
	ds_read_b128 v[222:225], v213 offset:8192
	ds_read_b128 v[226:229], v213 offset:12288
	v_cvt_pk_bf16_f32 v124, v80, v81
	v_cvt_pk_bf16_f32 v125, v82, v83
	v_cvt_pk_bf16_f32 v126, v84, v85
	v_cvt_pk_bf16_f32 v127, v86, v87
	v_cvt_pk_bf16_f32 v120, v88, v89
	v_cvt_pk_bf16_f32 v121, v90, v91
	v_cvt_pk_bf16_f32 v122, v92, v93
	v_cvt_pk_bf16_f32 v123, v94, v95
	v_cvt_pk_bf16_f32 v116, v64, v65
	v_cvt_pk_bf16_f32 v117, v66, v67
	v_cvt_pk_bf16_f32 v118, v68, v69
	v_cvt_pk_bf16_f32 v119, v70, v71
	v_cvt_pk_bf16_f32 v112, v72, v73
	v_cvt_pk_bf16_f32 v113, v74, v75
	v_cvt_pk_bf16_f32 v114, v76, v77
	v_cvt_pk_bf16_f32 v115, v78, v79
	s_branch .LBB0_561
